# bundle8 + P7/P8 tile order changed to 4 M-tiles x 8 N-tiles per XCD round (A operand read once per round)
# speedup vs baseline: 1.0113x; 1.0039x over previous
.LBB0_1313:
	v_lshrrev_b32_e32 v4, 1, v0
	v_lshrrev_b32_e32 v5, 5, v0
	v_lshlrev_b32_e32 v1, 4, v0
	v_and_b32_e32 v2, 32, v0
	v_and_b32_e32 v4, 24, v4
	v_and_b32_e32 v5, 4, v5
	v_bfe_u32 v6, v0, 2, 2
	v_bfe_u32 v13, v0, 2, 4
	v_bitop3_b32 v3, v1, v2, 48 bitop3:0x6c
	v_and_b32_e32 v12, 64, v0
	v_or3_b32 v4, v5, v6, v4
	v_lshrrev_b32_e32 v5, 3, v0
	v_or_b32_e32 v14, 0x2000, v1
	s_add_u32 s22, s26, 0x7000000
	v_or_b32_e32 v2, v3, v12
	v_and_or_b32 v6, v5, 48, v13
	v_and_or_b32 v5, v5, 32, v4
	v_lshrrev_b32_e32 v1, 7, v14
	s_movk_i32 s1, 0x70
	s_addc_u32 s23, s27, 0
	v_lshl_or_b32 v176, v5, 12, v2
	v_and_or_b32 v5, v1, s1, v13
	s_movk_i32 s1, 0x60
	s_add_i32 s0, s2, s0
	v_and_or_b32 v1, v1, s1, v4
	s_lshr_b32 s4, s0, 5
	s_lshl_b32 s4, s4, 2
	s_and_b32 s1, s0, 31
	s_lshr_b32 s2, s1, 2
	s_and_b32 s0, s1, 3
	s_add_i32 s38, s4, s0
	s_lshr_b32 s9, s3, 6
	s_ashr_i32 s39, s38, 31
	s_bfe_i64 s[4:5], s[2:3], 0x100000
	s_lshr_b32 s8, s3, 8
	s_lshl_b32 s28, s9, 10
	s_lshl_b64 s[0:1], s[38:39], 20
	s_lshl_b64 s[4:5], s[4:5], 20
	s_add_u32 s40, s22, s4
	s_addc_u32 s41, s23, s5
	s_add_i32 s29, s28, 0
	s_add_i32 m0, s29, 0x10000
	v_lshl_or_b32 v180, v1, 12, v2
	global_load_lds_dwordx4 v176, s[40:41]
	s_add_i32 m0, s29, 0x12000
	s_add_u32 s4, s40, 0x80000
	global_load_lds_dwordx4 v180, s[40:41]
	s_addc_u32 s5, s41, 0
	s_add_i32 m0, s29, 0x14000
	v_lshl_or_b32 v174, v6, 12, v2
	global_load_lds_dwordx4 v176, s[4:5]
	s_add_i32 m0, s29, 0x16000
	s_add_u32 s36, s50, s0
	s_addc_u32 s37, s51, s1
	s_add_i32 s44, s29, 0x2000
	global_load_lds_dwordx4 v180, s[4:5]
	s_mov_b32 m0, s29
	s_add_u32 s0, s36, 0x80000
	v_lshl_or_b32 v178, v5, 12, v2
	global_load_lds_dwordx4 v174, s[36:37]
	s_mov_b32 m0, s44
	s_addc_u32 s1, s37, 0
	s_add_i32 s45, s29, 0x4000
	global_load_lds_dwordx4 v178, s[36:37]
	s_mov_b32 m0, s45
	s_add_i32 s46, s29, 0x6000
	global_load_lds_dwordx4 v174, s[0:1]
	s_mov_b32 m0, s46
	v_mov_b32_e32 v2, 0
	global_load_lds_dwordx4 v178, s[0:1]
	v_mov_b32_e32 v177, v2
	v_mov_b32_e32 v181, v2
	v_mov_b32_e32 v175, v2
	v_mov_b32_e32 v179, v2
	s_cmp_eq_u32 s8, 1
	s_movk_i32 s47, 0x2000
	s_mov_b32 s48, 0
	v_lshl_add_u64 v[10:11], s[40:41], 0, v[176:177]
	v_lshl_add_u64 v[8:9], s[40:41], 0, v[180:181]
	v_lshl_add_u64 v[4:5], s[36:37], 0, v[174:175]
	s_cselect_b64 s[0:1], -1, 0
	s_cmp_lg_u32 s8, 1
	v_lshl_add_u64 v[6:7], s[36:37], 0, v[178:179]
	s_cbranch_scc1 .LBB0_1315
	s_barrier

.LBB0_1323:
	s_ashr_i32 s14, s16, 3
	s_add_i32 s14, s30, s14
	s_lshr_b32 s16, s14, 5
	s_lshl_b32 s16, s16, 2
	s_and_b32 s15, s14, 31
	s_lshr_b32 s14, s15, 2
	s_and_b32 s15, s15, 3
	s_add_i32 s16, s16, s15

.LBB0_1396:
	v_lshrrev_b32_e32 v3, 1, v0
	v_lshrrev_b32_e32 v4, 5, v0
	s_add_u32 s22, s26, 0x15c00000
	v_lshlrev_b32_e32 v1, 4, v0
	v_and_b32_e32 v2, 32, v0
	v_and_b32_e32 v3, 24, v3
	v_and_b32_e32 v4, 4, v4
	v_bfe_u32 v5, v0, 2, 2
	s_addc_u32 s23, s27, 0
	v_bfe_u32 v12, v0, 2, 4
	v_bitop3_b32 v10, v1, v2, 48 bitop3:0x6c
	v_and_b32_e32 v11, 64, v0
	v_or3_b32 v3, v4, v5, v3
	v_lshrrev_b32_e32 v4, 3, v0
	v_or_b32_e32 v13, 0x2000, v1
	s_add_u32 s28, s26, 0x7800000
	v_or_b32_e32 v2, v10, v11
	v_and_or_b32 v5, v4, 48, v12
	v_and_or_b32 v4, v4, 32, v3
	v_lshrrev_b32_e32 v1, 7, v13
	s_movk_i32 s1, 0x70
	s_addc_u32 s29, s27, 0
	v_lshl_or_b32 v148, v4, 12, v2
	v_and_or_b32 v4, v1, s1, v12
	s_movk_i32 s1, 0x60
	s_add_i32 s0, s2, s0
	v_and_or_b32 v1, v1, s1, v3
	s_lshr_b32 s6, s0, 5
	s_lshl_b32 s6, s6, 2
	s_and_b32 s1, s0, 31
	s_lshr_b32 s2, s1, 2
	s_and_b32 s0, s1, 3
	s_add_i32 s44, s6, s0
	s_lshr_b32 s5, s3, 6
	s_ashr_i32 s45, s44, 31
	s_bfe_i64 s[6:7], s[2:3], 0x100000
	s_lshr_b32 s4, s3, 8
	s_lshl_b32 s54, s5, 10
	s_lshl_b64 s[0:1], s[44:45], 20
	s_lshl_b64 s[6:7], s[6:7], 20
	s_add_u32 s48, s28, s6
	s_addc_u32 s49, s29, s7
	s_add_i32 s45, s54, 0
	s_add_i32 m0, s45, 0x10000
	v_lshl_or_b32 v152, v1, 12, v2
	global_load_lds_dwordx4 v148, s[48:49]
	s_add_i32 m0, s45, 0x12000
	s_add_u32 s6, s48, 0x80000
	global_load_lds_dwordx4 v152, s[48:49]
	s_addc_u32 s7, s49, 0
	s_add_i32 m0, s45, 0x14000
	v_lshl_or_b32 v146, v5, 12, v2
	global_load_lds_dwordx4 v148, s[6:7]
	s_add_i32 m0, s45, 0x16000
	s_add_u32 s46, s22, s0
	s_addc_u32 s47, s23, s1
	s_add_i32 s55, s45, 0x2000
	global_load_lds_dwordx4 v152, s[6:7]
	s_mov_b32 m0, s45
	s_add_u32 s0, s46, 0x80000
	v_lshl_or_b32 v150, v4, 12, v2
	global_load_lds_dwordx4 v146, s[46:47]
	s_mov_b32 m0, s55
	s_addc_u32 s1, s47, 0
	s_add_i32 s56, s45, 0x4000
	global_load_lds_dwordx4 v150, s[46:47]
	s_mov_b32 m0, s56
	s_add_i32 s57, s45, 0x6000
	global_load_lds_dwordx4 v146, s[0:1]
	s_mov_b32 m0, s57
	v_mov_b32_e32 v149, 0
	global_load_lds_dwordx4 v150, s[0:1]
	v_mov_b32_e32 v153, v149
	v_mov_b32_e32 v147, v149
	v_mov_b32_e32 v151, v149
	s_cmp_eq_u32 s4, 1
	s_mov_b32 s58, 0
	v_lshl_add_u64 v[8:9], s[48:49], 0, v[148:149]
	v_lshl_add_u64 v[6:7], s[48:49], 0, v[152:153]
	v_lshl_add_u64 v[2:3], s[46:47], 0, v[146:147]
	s_cselect_b64 s[0:1], -1, 0
	s_cmp_lg_u32 s4, 1
	v_lshl_add_u64 v[4:5], s[46:47], 0, v[150:151]
	s_cbranch_scc1 .LBB0_1398
	s_barrier

.LBB0_1406:
	s_ashr_i32 s36, s38, 3
	s_add_i32 s36, s40, s36
	s_lshr_b32 s38, s36, 5
	s_lshl_b32 s38, s38, 2
	s_and_b32 s37, s36, 31
	s_lshr_b32 s36, s37, 2
	s_and_b32 s37, s37, 3
	s_add_i32 s38, s38, s37
